# deferred phase-0 work split over three idle windows: A-in tail (b_w_in, w_q transposes on workgroups 128..255), after the A-out unit (w_k, w_v, b_w_out, all workgroups), B-in tail (gate folding on wor
# speedup vs baseline: 1.0091x; 1.0091x over previous
.Lp0_entry:
	s_mov_b64 s[0:1], s[96:97]
	s_load_dwordx4 s[16:19], s[0:1], 0x0
	s_load_dwordx2 s[24:25], s[0:1], 0x38
	s_load_dwordx2 s[30:31], s[0:1], 0x48
	s_load_dwordx4 s[4:7], s[0:1], 0x58
	s_load_dwordx8 s[8:15], s[0:1], 0x78
	s_load_dwordx2 s[26:27], s[0:1], 0xb0
	s_load_dwordx2 s[22:23], s[0:1], 0xc0
	v_mov_b32_e32 v2, v201
	s_mov_b32 s3, 0
	s_lshl_b64 s[0:1], s[2:3], 9
	v_ashrrev_i32_e32 v3, 31, v2
	v_lshl_add_u64 v[44:45], s[0:1], 0, v[2:3]
	s_cmp_lg_u32 s98, 0
	s_cbranch_scc1 .Lp0_skipzero
	s_mov_b64 s[0:1], 0x4c800
	v_cmp_gt_u64_e32 vcc, s[0:1], v[44:45]
	s_and_saveexec_b64 s[28:29], vcc
	s_cbranch_execz .LBB0_7
	s_ashr_i32 s53, s52, 31
	s_lshl_b64 s[34:35], s[52:53], 9
	s_lshl_b64 s[0:1], s[2:3], 11
	s_waitcnt lgkmcnt(0)
	s_add_u32 s0, s22, s0
	s_addc_u32 s1, s23, s1
	v_lshl_add_u64 v[4:5], v[2:3], 2, s[0:1]
	s_mov_b64 s[0:1], 0x3a20000
	v_lshl_add_u64 v[4:5], v[4:5], 0, s[0:1]
	s_lshl_b64 s[36:37], s[52:53], 11
	s_mov_b64 s[38:39], 0
	v_mov_b32_e32 v3, 0
	s_mov_b64 s[40:41], 0x4c7ff
	v_mov_b64_e32 v[6:7], v[44:45]

.Lp0_skipzero:
	v_ashrrev_i32_e32 v8, 6, v2
	s_lshl_b32 s0, s2, 3
	v_and_b32_e32 v47, 63, v2
	v_writelane_b32 v255, s0, 0
	v_add_u32_e32 v51, s0, v8
	s_movk_i32 s0, 0x3800
	s_lshl_b32 s33, s52, 3
	s_cmp_eq_u32 s98, 0
	s_cselect_b32 s0, 0x1400, s71
	s_cselect_b32 s33, s33, s72
	s_cselect_b32 s60, 0, s70
	v_add_u32_e32 v51, s60, v51
	v_cmp_gt_i32_e32 vcc, s0, v51
	v_lshlrev_b32_e32 v18, 3, v47
	s_and_saveexec_b64 s[28:29], vcc
	s_cbranch_execz .LBB0_34
	v_lshrrev_b32_e32 v19, 5, v47
	v_and_b32_e32 v26, 31, v2
	s_movk_i32 s0, 0x84
	v_mov_b32_e32 v2, 0x630
	v_mad_u32_u24 v35, v19, s0, v2
	v_mov_b32_e32 v2, 0xc60
	v_mad_u32_u24 v42, v19, s0, v2
	v_mov_b32_e32 v2, 0x1290
	v_mad_u32_u24 v53, v19, s0, v2
	v_mov_b32_e32 v2, 0x18c0
	v_mad_u32_u24 v60, v19, s0, v2
	v_and_b32_e32 v2, 56, v18
	v_lshrrev_b32_e32 v68, 3, v47
	v_mul_u32_u24_e32 v9, 0x84, v2
	v_lshlrev_b32_e32 v2, 1, v2
	v_mov_b32_e32 v3, 0
	v_lshl_add_u32 v7, v8, 14, 0
	s_waitcnt lgkmcnt(0)
	v_lshl_add_u64 v[4:5], s[22:23], 0, v[2:3]
	v_lshlrev_b32_e32 v2, 2, v68
	v_add3_u32 v69, v7, v9, v2
	v_lshlrev_b32_e32 v2, 5, v8
	v_lshl_add_u32 v74, s2, 8, v2
	v_lshlrev_b32_e32 v2, 7, v8
	v_lshlrev_b32_e32 v6, 2, v26
	v_lshl_add_u32 v75, s2, 10, v2
	v_lshlrev_b32_e32 v2, 6, v8
	v_add_u32_e32 v27, v7, v6
	v_mov_b32_e32 v7, v3
	v_lshl_add_u32 v76, s2, 9, v2
	v_lshlrev_b32_e32 v2, 1, v8
	s_mov_b64 s[36:37], 0x3600000
	s_mov_b64 s[38:39], 0x2d00000
	s_mov_b64 s[40:41], 0x2500000
	s_mov_b64 s[42:43], 0x1c00000
	s_mov_b64 s[44:45], 0x1400000
	s_mov_b64 s[46:47], 0x1000000
	v_lshl_add_u64 v[6:7], s[30:31], 0, v[6:7]
	s_add_u32 s30, s24, 0x1000
	v_lshl_add_u32 v2, s2, 4, v2
	v_mul_u32_u24_e32 v28, 0x84, v19
	v_or_b32_e32 v29, 2, v19
	v_or_b32_e32 v30, 4, v19
	v_or_b32_e32 v31, 6, v19
	v_or_b32_e32 v32, 8, v19
	v_or_b32_e32 v33, 10, v19
	v_or_b32_e32 v34, 12, v19
	v_or_b32_e32 v36, 14, v19
	v_or_b32_e32 v37, 16, v19
	v_or_b32_e32 v38, 18, v19
	v_or_b32_e32 v39, 20, v19
	v_or_b32_e32 v40, 22, v19
	v_or_b32_e32 v41, 24, v19
	v_or_b32_e32 v43, 26, v19
	v_or_b32_e32 v46, 28, v19
	v_or_b32_e32 v48, 30, v19
	v_or_b32_e32 v49, 32, v19
	v_or_b32_e32 v50, 34, v19
	v_or_b32_e32 v52, 36, v19
	v_or_b32_e32 v54, 38, v19
	v_or_b32_e32 v55, 40, v19
	v_or_b32_e32 v56, 42, v19
	v_or_b32_e32 v57, 44, v19
	v_or_b32_e32 v58, 46, v19
	v_or_b32_e32 v59, 48, v19
	v_or_b32_e32 v61, 50, v19
	v_or_b32_e32 v62, 52, v19
	v_or_b32_e32 v63, 54, v19
	v_or_b32_e32 v64, 56, v19
	v_or_b32_e32 v65, 58, v19
	v_or_b32_e32 v66, 60, v19
	v_or_b32_e32 v67, 62, v19
	v_or_b32_e32 v70, 8, v68
	v_or_b32_e32 v71, 16, v68
	v_or_b32_e32 v72, 24, v68
	v_bitop3_b32 v73, v68, 15, 24 bitop3:0xc8
	s_addc_u32 s31, s25, 0
	s_lshl_b32 s0, s33, 5
	s_lshl_b32 s1, s33, 7
	s_lshl_b32 s3, s33, 6
	v_add_u32_e32 v77, 0x19800, v2
	s_lshl_b32 s48, s33, 1
	s_mov_b64 s[34:35], 0
	s_movk_i32 s49, 0xfff
	s_movk_i32 s50, 0x13ff
	s_movk_i32 s51, 0x1bff
	s_movk_i32 s53, 0x23ff
	s_movk_i32 s54, 0x2bff
	s_movk_i32 s55, 0x33ff
	s_movk_i32 s56, 0x7fff
	s_mov_b32 s57, 0xffff0000
	s_movk_i32 s58, 0x37ff
	v_mov_b32_e32 v78, v51
	v_lshl_add_u64 v[8:9], v[4:5], 0, s[36:37]
	v_lshl_add_u64 v[10:11], v[4:5], 0, s[38:39]
	v_lshl_add_u64 v[12:13], v[4:5], 0, s[40:41]
	v_lshl_add_u64 v[14:15], v[4:5], 0, s[42:43]
	v_lshl_add_u64 v[16:17], v[4:5], 0, s[44:45]
	v_lshl_add_u64 v[20:21], v[4:5], 0, s[46:47]
	s_cmp_eq_u32 s98, 0
	s_cselect_b32 s58, 0x13ff, s75
	s_cselect_b32 s60, 0, s76
	s_cselect_b32 s61, 0, s77
	v_add_u32_e32 v74, s60, v74
	v_add_u32_e32 v75, s61, v75
	s_cselect_b32 s60, 0, s78
	s_cselect_b32 s61, 0, s79
	v_add_u32_e32 v76, s60, v76
	v_add_u32_e32 v77, s61, v77
	s_branch .LBB0_10

.LBB0_34:
	s_or_b64 exec, exec, s[28:29]
	s_cmp_eq_u32 s98, 0
	s_cselect_b32 s0, 0x4400, 0
	v_cmp_gt_i32_e32 vcc, s0, v51
	v_lshlrev_b32_e32 v46, 2, v47
	v_and_b32_e32 v208, 64, v200
	v_xor_b32_e32 v207, 1, v200
	v_xor_b32_e32 v206, 2, v200
	v_xor_b32_e32 v205, 4, v200
	v_xor_b32_e32 v204, 8, v200
	v_xor_b32_e32 v203, 16, v200
	v_xor_b32_e32 v202, 32, v200
	s_waitcnt lgkmcnt(0)
	s_and_saveexec_b64 s[6:7], vcc
	s_cbranch_execz .LBB0_41
	v_mov_b32_e32 v49, 0
	v_lshlrev_b32_e32 v48, 4, v47
	v_lshl_add_u64 v[20:21], s[24:25], 0, v[48:49]
	flat_load_dwordx4 v[2:5], v[20:21]
	flat_load_dwordx4 v[6:9], v[20:21] offset:1024
	flat_load_dwordx4 v[10:13], v[20:21] offset:2048
	flat_load_dwordx4 v[14:17], v[20:21] offset:3072
	v_add_u32_e32 v19, 64, v208
	v_cmp_lt_i32_e32 vcc, v207, v19
	s_mov_b64 s[4:5], 0x3b52000
	s_mov_b64 s[24:25], 0
	v_cndmask_b32_e32 v20, v200, v207, vcc
	v_cmp_lt_i32_e32 vcc, v206, v19
	s_movk_i32 s1, 0x3fff
	s_movk_i32 s3, 0x4000
	v_cndmask_b32_e32 v21, v200, v206, vcc
	v_cmp_lt_i32_e32 vcc, v205, v19
	s_mov_b32 s26, 0x3a800000
	s_mov_b32 s27, 0x800000
	v_cndmask_b32_e32 v22, v200, v205, vcc
	v_cmp_lt_i32_e32 vcc, v204, v19
	s_movk_i32 s28, 0x7fff
	s_movk_i32 s29, 0x43ff
	v_cndmask_b32_e32 v23, v200, v204, vcc
	v_cmp_lt_i32_e32 vcc, v203, v19
	v_mov_b32_e32 v50, 0x358637bd
	v_mov_b32_e32 v60, 1
	v_cndmask_b32_e32 v24, v200, v203, vcc
	v_cmp_lt_i32_e32 vcc, v202, v19
	v_mov_b32_e32 v19, v49
	v_lshl_add_u64 v[18:19], s[22:23], 0, v[18:19]
	v_cndmask_b32_e32 v25, v200, v202, vcc
	v_lshlrev_b32_e32 v48, 2, v46
	v_lshlrev_b32_e32 v61, 2, v20
	v_lshlrev_b32_e32 v62, 2, v21
	v_lshlrev_b32_e32 v63, 2, v22
	v_lshlrev_b32_e32 v64, 2, v23
	v_lshlrev_b32_e32 v65, 2, v24
	v_lshlrev_b32_e32 v66, 2, v25
	v_lshl_add_u64 v[52:53], v[18:19], 0, s[4:5]
	v_mov_b32_e32 v56, v51
	s_waitcnt vmcnt(0) lgkmcnt(0)
	v_mov_b32_e32 v54, v3
	v_mov_b32_e32 v55, v5
	v_mov_b32_e32 v3, v4
	v_mov_b32_e32 v4, v7
	v_mov_b32_e32 v5, v9
	v_mov_b32_e32 v7, v8
	v_mov_b32_e32 v8, v11
	v_mov_b32_e32 v9, v13
	v_mov_b32_e32 v11, v12
	v_mov_b32_e32 v12, v15
	v_mov_b32_e32 v13, v17
	v_mov_b32_e32 v15, v16
	s_branch .LBB0_37

.LBB0_41:
	s_or_b64 exec, exec, s[6:7]
	s_cmp_eq_u32 s98, 0
	s_cselect_b32 s0, 0, s74
	s_cselect_b32 s60, 0, s73
	v_subrev_u32_e32 v51, s60, v51
	v_cmp_gt_i32_e32 vcc, s0, v51
	s_and_saveexec_b64 s[16:17], vcc
	s_cbranch_execz .LBB0_51
	v_add_u32_e32 v2, 64, v208
	v_cmp_lt_i32_e32 vcc, v207, v2
	v_cmp_eq_u32_e64 s[4:5], 0, v47
	s_movk_i32 s1, 0x800
	v_cndmask_b32_e32 v3, v200, v207, vcc
	v_cmp_lt_i32_e32 vcc, v206, v2
	v_lshlrev_b32_e32 v24, 2, v3
	s_movk_i32 s3, 0x7ff
	v_cndmask_b32_e32 v3, v200, v206, vcc
	v_cmp_lt_i32_e32 vcc, v205, v2
	v_lshlrev_b32_e32 v25, 2, v3
	v_mov_b32_e32 v30, 0x20000
	v_cndmask_b32_e32 v3, v200, v205, vcc
	v_cmp_lt_i32_e32 vcc, v204, v2
	v_lshlrev_b32_e32 v26, 2, v3
	v_mov_b32_e32 v31, s9
	v_cndmask_b32_e32 v3, v200, v204, vcc
	v_cmp_lt_i32_e32 vcc, v203, v2
	v_lshlrev_b32_e32 v27, 2, v3
	v_mov_b32_e32 v32, s13
	v_cndmask_b32_e32 v3, v200, v203, vcc
	v_cmp_lt_i32_e32 vcc, v202, v2
	v_lshlrev_b32_e32 v28, 2, v3
	v_mov_b32_e32 v3, 0
	v_cndmask_b32_e32 v2, v200, v202, vcc
	v_lshlrev_b32_e32 v29, 2, v2
	v_lshlrev_b32_e32 v2, 5, v47
	v_mov_b32_e32 v47, v3
	v_lshl_add_u64 v[4:5], s[14:15], 0, v[2:3]
	v_lshl_add_u64 v[6:7], s[10:11], 0, v[46:47]
	s_mov_b64 s[10:11], 0
	v_mov_b32_e32 v33, s8
	v_mov_b32_e32 v34, s12
	s_movk_i32 s18, 0x2000
	s_movk_i32 s19, 0x3000
	s_mov_b64 s[8:9], 0x800
	s_mov_b32 s24, 0x11000
	s_mov_b32 s25, 0x12000
	s_mov_b32 s26, 0x13000
	s_movk_i32 s27, 0xfff
	s_movk_i32 s28, 0x7fff
	s_mov_b32 s29, 0x800000
	s_mov_b32 s30, 0x801000
	s_mov_b32 s31, 0x802000
	s_mov_b32 s34, 0x803000
	s_mov_b32 s35, 0x804000
	v_mov_b32_e32 v35, 0x2d00000
	v_mov_b32_e32 v36, 0x1c00000
	s_branch .LBB0_44

.LBB0_51:
	s_or_b64 exec, exec, s[16:17]
	s_mov_b64 s[0:1], 0x1f000
	s_cmp_eq_u32 s98, 0
	s_cselect_b32 s0, s0, 0
	v_cmp_gt_u64_e32 vcc, s[0:1], v[44:45]
	s_and_saveexec_b64 s[4:5], vcc
	s_cbranch_execz .LBB0_54
	s_ashr_i32 s53, s52, 31
	s_mov_b32 s10, 0xffff0800
	v_mov_b32_e32 v3, 0
	s_lshl_b64 s[6:7], s[52:53], 9
	s_mov_b64 s[8:9], 0
	s_mov_b32 s11, -1
	s_mov_b64 s[12:13], 0xf800
	v_mov_b32_e32 v4, 0x2d00000
	v_mov_b32_e32 v5, 0x1c00000
	v_mov_b32_e32 v6, v3
	v_mov_b32_e32 v7, v3
	v_mov_b32_e32 v8, v3
	v_mov_b32_e32 v9, v3
	s_mov_b64 s[14:15], 0x1efff

.LBB0_54:
	s_or_b64 exec, exec, s[4:5]
	s_cmp_eq_u32 s98, 0
	s_cbranch_scc1 .Lp0_first
	s_lshl_b32 s33, s52, 3
	s_ashr_i32 s53, s52, 31
	s_mov_b32 s3, 0
	s_cmp_eq_u32 s98, 1
	s_cbranch_scc1 .Lp3_resume
	s_cmp_eq_u32 s98, 2
	s_cbranch_scc1 .Lp4_resume
	s_branch .Lp1_resume

.LBB0_232:
	s_cmp_lt_u32 s2, 0x80
	s_cbranch_scc1 .Lp1_resume
	s_mov_b32 s98, 3
	s_mov_b32 s70, 0x1000
	s_mov_b32 s71, 0x2400
	s_mov_b32 s72, 0x400
	s_mov_b32 s73, 0x0
	s_mov_b32 s74, 0x0
	s_mov_b32 s75, 0x23ff
	s_lshl_b32 s76, s70, 5
	s_lshl_b32 s77, s70, 7
	s_lshl_b32 s78, s70, 6
	s_lshl_b32 s79, s70, 1
	s_branch .Lp0_entry
.Lp1_resume:
	s_mov_b32 s98, 0
	s_mov_b64 s[4:5], s[96:97]
	s_waitcnt vmcnt(0)
	v_mov_b32_e32 v0, v201
	s_waitcnt lgkmcnt(0)
	s_barrier
	s_nop 0
	v_cmp_eq_u32_e32 vcc, 0, v0
	s_and_saveexec_b64 s[36:37], vcc
	s_cbranch_execz .LBB0_276
	s_add_i32 s1, 0, 0x25fc0
	v_mov_b32_e32 v0, s1
	s_load_dwordx2 s[38:39], s[4:5], 0xc0
	s_getreg_b32 s0, hwreg(HW_REG_XCC_ID, 0, 4)
	s_waitcnt vmcnt(0) expcnt(0) lgkmcnt(0)
	ds_read_b32 v2, v0
	s_add_i32 s1, 0, 0x25fc4
	v_mov_b32_e32 v0, s1
	ds_read_b32 v0, v0
	s_and_b32 s0, s0, 15
	s_waitcnt lgkmcnt(1)
	v_cmp_ne_u32_e32 vcc, 0, v2
	s_cbranch_vccnz .LBB0_247
	s_add_u32 s4, s38, 0x44752200
	s_addc_u32 s5, s39, 0
	s_add_u32 s8, s38, 0x44752400
	s_addc_u32 s9, s39, 0
	s_add_u32 s10, s38, 0x44752500
	s_addc_u32 s11, s39, 0
	s_add_u32 s12, s38, 0x44752600
	s_addc_u32 s13, s39, 0
	s_add_u32 s14, s38, 0x44752700
	s_addc_u32 s15, s39, 0
	s_add_u32 s16, s38, 0x44752800
	s_addc_u32 s17, s39, 0
	s_add_u32 s18, s38, 0x44752900
	s_addc_u32 s19, s39, 0
	s_add_u32 s20, s38, 0x44752a00
	s_addc_u32 s21, s39, 0
	s_add_u32 s22, s38, 0x44752b00
	s_addc_u32 s23, s39, 0
	s_add_u32 s24, s38, 0x44752c00
	s_addc_u32 s25, s39, 0
	s_add_u32 s26, s38, 0x44752d00
	s_addc_u32 s27, s39, 0
	s_add_u32 s28, s38, 0x44752e00
	s_addc_u32 s29, s39, 0
	s_add_u32 s30, s38, 0x44752f00
	s_addc_u32 s31, s39, 0
	s_add_u32 s34, s38, 0x44753000
	s_addc_u32 s35, s39, 0
	s_add_u32 s40, s38, 0x44753100
	s_addc_u32 s41, s39, 0
	s_add_u32 s42, s38, 0x44753200
	s_addc_u32 s43, s39, 0
	s_add_u32 s44, s38, 0x44753300
	s_addc_u32 s45, s39, 0
	s_mov_b32 s1, 1
	s_mov_b64 s[6:7], 0
	s_waitcnt lgkmcnt(0)
	v_mov_b64_e32 v[0:1], s[8:9]
	v_mov_b64_e32 v[2:3], s[10:11]
	v_mov_b64_e32 v[4:5], s[12:13]
	v_mov_b64_e32 v[6:7], s[14:15]
	v_mov_b64_e32 v[8:9], s[16:17]
	v_mov_b64_e32 v[10:11], s[18:19]
	v_mov_b64_e32 v[12:13], s[20:21]
	v_mov_b64_e32 v[14:15], s[22:23]
	v_mov_b64_e32 v[16:17], s[24:25]
	v_mov_b64_e32 v[18:19], s[26:27]
	v_mov_b64_e32 v[20:21], s[28:29]
	v_mov_b64_e32 v[22:23], s[30:31]
	v_mov_b64_e32 v[24:25], s[34:35]
	v_mov_b64_e32 v[26:27], s[40:41]
	v_mov_b64_e32 v[28:29], s[42:43]
	v_mov_b64_e32 v[30:31], s[44:45]
	s_branch .LBB0_237

.LBB0_354:
	s_mov_b32 s98, 1
	s_mov_b32 s70, 0x2400
	s_mov_b32 s71, 0x3800
	s_mov_b32 s72, 0x800
	s_mov_b32 s73, 0x0
	s_mov_b32 s74, 0x0
	s_mov_b32 s75, 0x37ff
	s_lshl_b32 s76, s70, 5
	s_lshl_b32 s77, s70, 7
	s_lshl_b32 s78, s70, 6
	s_lshl_b32 s79, s70, 1
	s_branch .Lp0_entry
.Lp3_resume:
	s_mov_b32 s98, 0
	s_mov_b64 s[6:7], s[96:97]
	s_waitcnt vmcnt(0)
	v_mov_b32_e32 v0, v201
	s_waitcnt lgkmcnt(0)
	s_barrier
	s_nop 0
	v_cmp_eq_u32_e32 vcc, 0, v0
	s_and_saveexec_b64 s[38:39], vcc
	s_cbranch_execz .LBB0_398
	s_add_i32 s1, 0, 0x25fc0
	v_mov_b32_e32 v0, s1
	s_load_dwordx2 s[40:41], s[6:7], 0xc0
	s_getreg_b32 s0, hwreg(HW_REG_XCC_ID, 0, 4)
	s_waitcnt vmcnt(0) expcnt(0) lgkmcnt(0)
	ds_read_b32 v2, v0
	s_add_i32 s1, 0, 0x25fc4
	v_mov_b32_e32 v0, s1
	ds_read_b32 v0, v0
	s_and_b32 s0, s0, 15
	s_waitcnt lgkmcnt(1)
	v_cmp_ne_u32_e32 vcc, 0, v2
	s_cbranch_vccnz .LBB0_369
	s_add_u32 s6, s40, 0x44752200
	s_addc_u32 s7, s41, 0
	s_add_u32 s4, s40, 0x44752400
	s_addc_u32 s5, s41, 0
	s_add_u32 s10, s40, 0x44752500
	s_addc_u32 s11, s41, 0
	s_add_u32 s12, s40, 0x44752600
	s_addc_u32 s13, s41, 0
	s_add_u32 s14, s40, 0x44752700
	s_addc_u32 s15, s41, 0
	s_add_u32 s16, s40, 0x44752800
	s_addc_u32 s17, s41, 0
	s_add_u32 s18, s40, 0x44752900
	s_addc_u32 s19, s41, 0
	s_add_u32 s20, s40, 0x44752a00
	s_addc_u32 s21, s41, 0
	s_add_u32 s22, s40, 0x44752b00
	s_addc_u32 s23, s41, 0
	s_add_u32 s24, s40, 0x44752c00
	s_addc_u32 s25, s41, 0
	s_add_u32 s26, s40, 0x44752d00
	s_addc_u32 s27, s41, 0
	s_add_u32 s28, s40, 0x44752e00
	s_addc_u32 s29, s41, 0
	s_add_u32 s30, s40, 0x44752f00
	s_addc_u32 s31, s41, 0
	s_add_u32 s34, s40, 0x44753000
	s_addc_u32 s35, s41, 0
	s_add_u32 s36, s40, 0x44753100
	s_addc_u32 s37, s41, 0
	s_add_u32 s42, s40, 0x44753200
	s_addc_u32 s43, s41, 0
	s_add_u32 s44, s40, 0x44753300
	s_addc_u32 s45, s41, 0
	s_mov_b32 s1, 1
	s_mov_b64 s[8:9], 0
	s_waitcnt lgkmcnt(0)
	v_mov_b64_e32 v[0:1], s[4:5]
	v_mov_b64_e32 v[2:3], s[10:11]
	v_mov_b64_e32 v[4:5], s[12:13]
	v_mov_b64_e32 v[6:7], s[14:15]
	v_mov_b64_e32 v[8:9], s[16:17]
	v_mov_b64_e32 v[10:11], s[18:19]
	v_mov_b64_e32 v[12:13], s[20:21]
	v_mov_b64_e32 v[14:15], s[22:23]
	v_mov_b64_e32 v[16:17], s[24:25]
	v_mov_b64_e32 v[18:19], s[26:27]
	v_mov_b64_e32 v[20:21], s[28:29]
	v_mov_b64_e32 v[22:23], s[30:31]
	v_mov_b64_e32 v[24:25], s[34:35]
	v_mov_b64_e32 v[26:27], s[36:37]
	v_mov_b64_e32 v[28:29], s[42:43]
	v_mov_b64_e32 v[30:31], s[44:45]
	s_branch .LBB0_359

.LBB0_540:
	s_cmp_lt_u32 s2, 0x40
	s_cbranch_scc1 .Lp4_resume
	s_mov_b32 s98, 2
	s_mov_b32 s70, 0x0
	s_mov_b32 s71, 0x0
	s_mov_b32 s72, 0x600
	s_mov_b32 s73, 0x200
	s_mov_b32 s74, 0x1000
	s_mov_b32 s75, 0xffffffff
	s_lshl_b32 s76, s70, 5
	s_lshl_b32 s77, s70, 7
	s_lshl_b32 s78, s70, 6
	s_lshl_b32 s79, s70, 1
	s_branch .Lp0_entry
